# EpiResid (out-proj, down) rewritten by hand: 16-byte residual loads and XB stores via v_permlane16_swap pairs, 6 row groups of loads in flight
# speedup vs baseline: 1.0329x; 1.0260x over previous
; __device__ __forceinline__ float bf_lo(unsigned u) { return __uint_as_float(u << 16); }
; __device__ __forceinline__ float bf_hi(unsigned u) { return __uint_as_float(u & 0xffff0000u); }
; __device__ __forceinline__ unsigned pk_bf16(float lo, float hi) { const f32x2 v = {lo, hi}; const bf16x2_t b = __builtin_convertvector(v, bf16x2_t); return __builtin_bit_cast(unsigned, b); }
;     __device__ __forceinline__ void operator()(const f32x4 (&acc)[2][2][4][2], const pg8::Unit& u, int wr, int wc, int fr, int fq) const {
;         asm volatile("" : "+v"(fr));
;         const int row0 = u.pm * 256 + wr * 64 + fr, col0 = u.pn * 256 + wc * 32 + 4 * fq;
;         const bool rf32 = (rp != nullptr) && (u.pm < MP / 256);
; #pragma unroll
;         for (int ai = 0; ai < 2; ++ai)
; #pragma unroll
;             for (int m = 0; m < 4; ++m) {
;                 const int row = row0 + ai * 128 + m * 16; const size_t off = (size_t)row * DM + col0; float q = 0.f;
;                 f32x4 r4[2][2];
;                 if (rf32) {
; #pragma unroll
;                     for (int bj = 0; bj < 2; ++bj)
; #pragma unroll
;                         for (int n = 0; n < 2; ++n) r4[bj][n] = *(const f32x4*)(rp + off + bj * 128 + n * 16);
;                 } else {
; #pragma unroll
;                     for (int bj = 0; bj < 2; ++bj)
; #pragma unroll
;                         for (int n = 0; n < 2; ++n) { const u32x2 w = *(const u32x2*)(XB + off + bj * 128 + n * 16); r4[bj][n] = (f32x4){bf_lo(w.x), bf_hi(w.x), bf_lo(w.y), bf_hi(w.y)}; }
;                 }
; #pragma unroll
;                 for (int bj = 0; bj < 2; ++bj)
; #pragma unroll
;                     for (int n = 0; n < 2; ++n) { const f32x4 x4 = r4[bj][n] + acc[ai][bj][m][n];
;                         q += (x4[0] * x4[0] + x4[1] * x4[1]) + (x4[2] * x4[2] + x4[3] * x4[3]);
;                         u32x2 w; w.x = pk_bf16(x4[0], x4[1]); w.y = pk_bf16(x4[2], x4[3]); *(u32x2*)(XB + off + bj * 128 + n * 16) = w; }
;                 q += __shfl_xor(q, 16); q += __shfl_xor(q, 32);
;                 if (fq == 0) ssq[(size_t)row * 16 + u.pn * 4 + wc] = q;
.LBB0_1683:
	s_lshl_b32 s4, s51, 8
	v_mov_b32_e32 v158, v1
	s_add_i32 s4, s4, s46
	s_lshl_b32 s28, s50, 2
	v_add_u32_e32 v160, s4, v158
	v_ashrrev_i32_e32 v161, 31, v160
	v_lshl_or_b32 v158, s50, 8, v163
	v_lshlrev_b64 v[166:167], 11, v[160:161]
	v_ashrrev_i32_e32 v159, 31, v158
	v_lshl_add_u64 v[166:167], s[14:15], 0, v[166:167]
	v_lshl_add_u64 v[166:167], v[158:159], 1, v[166:167]
	s_ashr_i32 s29, s28, 31
	v_lshlrev_b32_e32 v252, 11, v160
	v_lshl_add_u32 v252, v158, 1, v252
	v_bfe_u32 v253, v190, 4, 1
	v_mul_u32_u24_e32 v253, 24, v253
	v_add_u32_e32 v252, v252, v253
	s_lshl_b32 s88, s45, 2
	v_lshl_add_u32 v189, v160, 6, s88
	v_lshl_add_u32 v189, s28, 2, v189
	global_load_dwordx4 v[204:207], v252, s[14:15]
	global_load_dwordx4 v[208:211], v252, s[14:15] offset:256
	v_add_u32_e32 v253, 0x8000, v252
	global_load_dwordx4 v[212:215], v253, s[14:15]
	global_load_dwordx4 v[216:219], v253, s[14:15] offset:256
	v_add_u32_e32 v253, 0x10000, v252
	global_load_dwordx4 v[220:223], v253, s[14:15]
	global_load_dwordx4 v[224:227], v253, s[14:15] offset:256
	v_add_u32_e32 v253, 0x18000, v252
	global_load_dwordx4 v[228:231], v253, s[14:15]
	global_load_dwordx4 v[232:235], v253, s[14:15] offset:256
	v_add_u32_e32 v253, 0x40000, v252
	global_load_dwordx4 v[236:239], v253, s[14:15]
	global_load_dwordx4 v[240:243], v253, s[14:15] offset:256
	v_add_u32_e32 v253, 0x48000, v252
	global_load_dwordx4 v[244:247], v253, s[14:15]
	global_load_dwordx4 v[248:251], v253, s[14:15] offset:256
	s_waitcnt vmcnt(10)
	v_permlane16_swap_b32_e32 v204, v206
	v_permlane16_swap_b32_e32 v205, v207
	v_permlane16_swap_b32_e32 v208, v210
	v_permlane16_swap_b32_e32 v209, v211
	v_lshlrev_b32_e32 v166, 16, v204
	v_and_b32_e32 v167, 0xffff0000, v204
	v_lshlrev_b32_e32 v168, 16, v205
	v_and_b32_e32 v169, 0xffff0000, v205
	v_lshlrev_b32_e32 v170, 16, v206
	v_and_b32_e32 v171, 0xffff0000, v206
	v_lshlrev_b32_e32 v172, 16, v207
	v_and_b32_e32 v173, 0xffff0000, v207
	v_lshlrev_b32_e32 v174, 16, v208
	v_and_b32_e32 v175, 0xffff0000, v208
	v_lshlrev_b32_e32 v176, 16, v209
	v_and_b32_e32 v177, 0xffff0000, v209
	v_lshlrev_b32_e32 v178, 16, v210
	v_and_b32_e32 v179, 0xffff0000, v210
	v_lshlrev_b32_e32 v180, 16, v211
	v_and_b32_e32 v181, 0xffff0000, v211
	v_pk_add_f32 v[126:127], v[126:127], v[166:167]
	v_pk_add_f32 v[128:129], v[128:129], v[168:169]
	v_pk_add_f32 v[122:123], v[122:123], v[170:171]
	v_pk_add_f32 v[124:125], v[124:125], v[172:173]
	v_pk_add_f32 v[118:119], v[118:119], v[174:175]
	v_pk_add_f32 v[120:121], v[120:121], v[176:177]
	v_pk_add_f32 v[114:115], v[114:115], v[178:179]
	v_pk_add_f32 v[116:117], v[116:117], v[180:181]
	v_add_u32_e32 v253, 0x50000, v252
	global_load_dwordx4 v[204:207], v253, s[14:15]
	global_load_dwordx4 v[208:211], v253, s[14:15] offset:256
	v_cvt_pk_bf16_f32 v166, v126, v127
	v_cvt_pk_bf16_f32 v167, v128, v129
	v_cvt_pk_bf16_f32 v168, v122, v123
	v_cvt_pk_bf16_f32 v169, v124, v125
	v_cvt_pk_bf16_f32 v170, v118, v119
	v_cvt_pk_bf16_f32 v171, v120, v121
	v_cvt_pk_bf16_f32 v172, v114, v115
	v_cvt_pk_bf16_f32 v173, v116, v117
	v_mul_f32_e32 v174, v126, v126
	v_mul_f32_e32 v175, v122, v122
	v_mul_f32_e32 v176, v118, v118
	v_mul_f32_e32 v177, v114, v114
	v_fmac_f32_e32 v174, v127, v127
	v_fmac_f32_e32 v175, v123, v123
	v_fmac_f32_e32 v176, v119, v119
	v_fmac_f32_e32 v177, v115, v115
	v_fmac_f32_e32 v174, v128, v128
	v_fmac_f32_e32 v175, v124, v124
	v_fmac_f32_e32 v176, v120, v120
	v_fmac_f32_e32 v177, v116, v116
	v_fmac_f32_e32 v174, v129, v129
	v_fmac_f32_e32 v175, v125, v125
	v_fmac_f32_e32 v176, v121, v121
	v_fmac_f32_e32 v177, v117, v117
	v_add_f32_e32 v174, v174, v175
	v_add_f32_e32 v176, v176, v177
	v_add_f32_e32 v178, v174, v176
	ds_bpermute_b32 v179, v131, v178
	v_permlane16_swap_b32_e32 v166, v168
	v_permlane16_swap_b32_e32 v167, v169
	v_permlane16_swap_b32_e32 v170, v172
	v_permlane16_swap_b32_e32 v171, v173
	global_store_dwordx4 v252, v[166:169], s[14:15]
	global_store_dwordx4 v252, v[170:173], s[14:15] offset:256
	s_waitcnt lgkmcnt(0)
	v_add_f32_e32 v178, v178, v179
	ds_bpermute_b32 v179, v135, v178
	s_waitcnt lgkmcnt(0)
	v_add_f32_e32 v178, v178, v179
	s_and_saveexec_b64 s[30:31], s[8:9]
	global_store_dword v189, v178, s[16:17]
	s_or_b64 exec, exec, s[30:31]
	s_waitcnt vmcnt(12)
	v_permlane16_swap_b32_e32 v212, v214
	v_permlane16_swap_b32_e32 v213, v215
	v_permlane16_swap_b32_e32 v216, v218
	v_permlane16_swap_b32_e32 v217, v219
	v_lshlrev_b32_e32 v166, 16, v212
	v_and_b32_e32 v167, 0xffff0000, v212
	v_lshlrev_b32_e32 v168, 16, v213
	v_and_b32_e32 v169, 0xffff0000, v213
	v_lshlrev_b32_e32 v170, 16, v214
	v_and_b32_e32 v171, 0xffff0000, v214
	v_lshlrev_b32_e32 v172, 16, v215
	v_and_b32_e32 v173, 0xffff0000, v215
	v_lshlrev_b32_e32 v174, 16, v216
	v_and_b32_e32 v175, 0xffff0000, v216
	v_lshlrev_b32_e32 v176, 16, v217
	v_and_b32_e32 v177, 0xffff0000, v217
	v_lshlrev_b32_e32 v178, 16, v218
	v_and_b32_e32 v179, 0xffff0000, v218
	v_lshlrev_b32_e32 v180, 16, v219
	v_and_b32_e32 v181, 0xffff0000, v219
	v_pk_add_f32 v[110:111], v[110:111], v[166:167]
	v_pk_add_f32 v[112:113], v[112:113], v[168:169]
	v_pk_add_f32 v[106:107], v[106:107], v[170:171]
	v_pk_add_f32 v[108:109], v[108:109], v[172:173]
	v_pk_add_f32 v[102:103], v[102:103], v[174:175]
	v_pk_add_f32 v[104:105], v[104:105], v[176:177]
	v_pk_add_f32 v[98:99], v[98:99], v[178:179]
	v_pk_add_f32 v[100:101], v[100:101], v[180:181]
	v_add_u32_e32 v253, 0x58000, v252
	global_load_dwordx4 v[212:215], v253, s[14:15]
	global_load_dwordx4 v[216:219], v253, s[14:15] offset:256
	v_cvt_pk_bf16_f32 v166, v110, v111
	v_cvt_pk_bf16_f32 v167, v112, v113
	v_cvt_pk_bf16_f32 v168, v106, v107
	v_cvt_pk_bf16_f32 v169, v108, v109
	v_cvt_pk_bf16_f32 v170, v102, v103
	v_cvt_pk_bf16_f32 v171, v104, v105
	v_cvt_pk_bf16_f32 v172, v98, v99
	v_cvt_pk_bf16_f32 v173, v100, v101
	v_mul_f32_e32 v174, v110, v110
	v_mul_f32_e32 v175, v106, v106
	v_mul_f32_e32 v176, v102, v102
	v_mul_f32_e32 v177, v98, v98
	v_fmac_f32_e32 v174, v111, v111
	v_fmac_f32_e32 v175, v107, v107
	v_fmac_f32_e32 v176, v103, v103
	v_fmac_f32_e32 v177, v99, v99
	v_fmac_f32_e32 v174, v112, v112
	v_fmac_f32_e32 v175, v108, v108
	v_fmac_f32_e32 v176, v104, v104
	v_fmac_f32_e32 v177, v100, v100
	v_fmac_f32_e32 v174, v113, v113
	v_fmac_f32_e32 v175, v109, v109
	v_fmac_f32_e32 v176, v105, v105
	v_fmac_f32_e32 v177, v101, v101
	v_add_f32_e32 v174, v174, v175
	v_add_f32_e32 v176, v176, v177
	v_add_f32_e32 v178, v174, v176
	ds_bpermute_b32 v179, v131, v178
	v_permlane16_swap_b32_e32 v166, v168
	v_permlane16_swap_b32_e32 v167, v169
	v_permlane16_swap_b32_e32 v170, v172
	v_permlane16_swap_b32_e32 v171, v173
	v_add_u32_e32 v253, 0x8000, v252
	global_store_dwordx4 v253, v[166:169], s[14:15]
	global_store_dwordx4 v253, v[170:173], s[14:15] offset:256
	s_waitcnt lgkmcnt(0)
; __device__ __forceinline__ float bf_lo(unsigned u) { return __uint_as_float(u << 16); }
; __device__ __forceinline__ float bf_hi(unsigned u) { return __uint_as_float(u & 0xffff0000u); }
; __device__ __forceinline__ unsigned pk_bf16(float lo, float hi) { const f32x2 v = {lo, hi}; const bf16x2_t b = __builtin_convertvector(v, bf16x2_t); return __builtin_bit_cast(unsigned, b); }
;     __device__ __forceinline__ void operator()(const f32x4 (&acc)[2][2][4][2], const pg8::Unit& u, int wr, int wc, int fr, int fq) const {
;     ...
;         for (int ai = 0; ai < 2; ++ai)
; #pragma unroll
;             for (int m = 0; m < 4; ++m) {
;                 const int row = row0 + ai * 128 + m * 16; const size_t off = (size_t)row * DM + col0; float q = 0.f;
;                 f32x4 r4[2][2];
;                 if (rf32) {
; #pragma unroll
;                     for (int bj = 0; bj < 2; ++bj)
; #pragma unroll
;                         for (int n = 0; n < 2; ++n) r4[bj][n] = *(const f32x4*)(rp + off + bj * 128 + n * 16);
;                 } else {
; #pragma unroll
;                     for (int bj = 0; bj < 2; ++bj)
; #pragma unroll
;                         for (int n = 0; n < 2; ++n) { const u32x2 w = *(const u32x2*)(XB + off + bj * 128 + n * 16); r4[bj][n] = (f32x4){bf_lo(w.x), bf_hi(w.x), bf_lo(w.y), bf_hi(w.y)}; }
;                 }
; #pragma unroll
;                 for (int bj = 0; bj < 2; ++bj)
; #pragma unroll
;                     for (int n = 0; n < 2; ++n) { const f32x4 x4 = r4[bj][n] + acc[ai][bj][m][n];
;                         q += (x4[0] * x4[0] + x4[1] * x4[1]) + (x4[2] * x4[2] + x4[3] * x4[3]);
;                         u32x2 w; w.x = pk_bf16(x4[0], x4[1]); w.y = pk_bf16(x4[2], x4[3]); *(u32x2*)(XB + off + bj * 128 + n * 16) = w; }
;                 q += __shfl_xor(q, 16); q += __shfl_xor(q, 32);
;                 if (fq == 0) ssq[(size_t)row * 16 + u.pn * 4 + wc] = q;
	v_add_f32_e32 v178, v178, v179
	ds_bpermute_b32 v179, v135, v178
	s_waitcnt lgkmcnt(0)
	v_add_f32_e32 v178, v178, v179
	s_and_saveexec_b64 s[30:31], s[8:9]
	global_store_dword v189, v178, s[16:17] offset:1024
	s_or_b64 exec, exec, s[30:31]
	s_waitcnt vmcnt(14)
	v_permlane16_swap_b32_e32 v220, v222
	v_permlane16_swap_b32_e32 v221, v223
	v_permlane16_swap_b32_e32 v224, v226
	v_permlane16_swap_b32_e32 v225, v227
	v_lshlrev_b32_e32 v166, 16, v220
	v_and_b32_e32 v167, 0xffff0000, v220
	v_lshlrev_b32_e32 v168, 16, v221
	v_and_b32_e32 v169, 0xffff0000, v221
	v_lshlrev_b32_e32 v170, 16, v222
	v_and_b32_e32 v171, 0xffff0000, v222
	v_lshlrev_b32_e32 v172, 16, v223
	v_and_b32_e32 v173, 0xffff0000, v223
	v_lshlrev_b32_e32 v174, 16, v224
	v_and_b32_e32 v175, 0xffff0000, v224
	v_lshlrev_b32_e32 v176, 16, v225
	v_and_b32_e32 v177, 0xffff0000, v225
	v_lshlrev_b32_e32 v178, 16, v226
	v_and_b32_e32 v179, 0xffff0000, v226
	v_lshlrev_b32_e32 v180, 16, v227
	v_and_b32_e32 v181, 0xffff0000, v227
	v_pk_add_f32 v[94:95], v[94:95], v[166:167]
	v_pk_add_f32 v[96:97], v[96:97], v[168:169]
	v_pk_add_f32 v[90:91], v[90:91], v[170:171]
	v_pk_add_f32 v[92:93], v[92:93], v[172:173]
	v_pk_add_f32 v[86:87], v[86:87], v[174:175]
	v_pk_add_f32 v[88:89], v[88:89], v[176:177]
	v_pk_add_f32 v[82:83], v[82:83], v[178:179]
	v_pk_add_f32 v[84:85], v[84:85], v[180:181]
	v_cvt_pk_bf16_f32 v166, v94, v95
	v_cvt_pk_bf16_f32 v167, v96, v97
	v_cvt_pk_bf16_f32 v168, v90, v91
	v_cvt_pk_bf16_f32 v169, v92, v93
	v_cvt_pk_bf16_f32 v170, v86, v87
	v_cvt_pk_bf16_f32 v171, v88, v89
	v_cvt_pk_bf16_f32 v172, v82, v83
	v_cvt_pk_bf16_f32 v173, v84, v85
	v_mul_f32_e32 v174, v94, v94
	v_mul_f32_e32 v175, v90, v90
	v_mul_f32_e32 v176, v86, v86
	v_mul_f32_e32 v177, v82, v82
	v_fmac_f32_e32 v174, v95, v95
	v_fmac_f32_e32 v175, v91, v91
	v_fmac_f32_e32 v176, v87, v87
	v_fmac_f32_e32 v177, v83, v83
	v_fmac_f32_e32 v174, v96, v96
	v_fmac_f32_e32 v175, v92, v92
	v_fmac_f32_e32 v176, v88, v88
	v_fmac_f32_e32 v177, v84, v84
	v_fmac_f32_e32 v174, v97, v97
	v_fmac_f32_e32 v175, v93, v93
	v_fmac_f32_e32 v176, v89, v89
	v_fmac_f32_e32 v177, v85, v85
	v_add_f32_e32 v174, v174, v175
	v_add_f32_e32 v176, v176, v177
	v_add_f32_e32 v178, v174, v176
	ds_bpermute_b32 v179, v131, v178
	v_permlane16_swap_b32_e32 v166, v168
	v_permlane16_swap_b32_e32 v167, v169
	v_permlane16_swap_b32_e32 v170, v172
	v_permlane16_swap_b32_e32 v171, v173
	v_add_u32_e32 v253, 0x10000, v252
	global_store_dwordx4 v253, v[166:169], s[14:15]
	global_store_dwordx4 v253, v[170:173], s[14:15] offset:256
	s_waitcnt lgkmcnt(0)
	v_add_f32_e32 v178, v178, v179
	ds_bpermute_b32 v179, v135, v178
	s_waitcnt lgkmcnt(0)
	v_add_f32_e32 v178, v178, v179
	s_and_saveexec_b64 s[30:31], s[8:9]
	global_store_dword v189, v178, s[16:17] offset:2048
	s_or_b64 exec, exec, s[30:31]
	s_waitcnt vmcnt(14)
	v_permlane16_swap_b32_e32 v228, v230
	v_permlane16_swap_b32_e32 v229, v231
	v_permlane16_swap_b32_e32 v232, v234
	v_permlane16_swap_b32_e32 v233, v235
	v_lshlrev_b32_e32 v166, 16, v228
	v_and_b32_e32 v167, 0xffff0000, v228
	v_lshlrev_b32_e32 v168, 16, v229
	v_and_b32_e32 v169, 0xffff0000, v229
	v_lshlrev_b32_e32 v170, 16, v230
	v_and_b32_e32 v171, 0xffff0000, v230
	v_lshlrev_b32_e32 v172, 16, v231
	v_and_b32_e32 v173, 0xffff0000, v231
	v_lshlrev_b32_e32 v174, 16, v232
	v_and_b32_e32 v175, 0xffff0000, v232
	v_lshlrev_b32_e32 v176, 16, v233
	v_and_b32_e32 v177, 0xffff0000, v233
	v_lshlrev_b32_e32 v178, 16, v234
	v_and_b32_e32 v179, 0xffff0000, v234
	v_lshlrev_b32_e32 v180, 16, v235
	v_and_b32_e32 v181, 0xffff0000, v235
	v_pk_add_f32 v[78:79], v[78:79], v[166:167]
	v_pk_add_f32 v[80:81], v[80:81], v[168:169]
	v_pk_add_f32 v[74:75], v[74:75], v[170:171]
	v_pk_add_f32 v[76:77], v[76:77], v[172:173]
	v_pk_add_f32 v[70:71], v[70:71], v[174:175]
	v_pk_add_f32 v[72:73], v[72:73], v[176:177]
	v_pk_add_f32 v[66:67], v[66:67], v[178:179]
	v_pk_add_f32 v[68:69], v[68:69], v[180:181]
	v_cvt_pk_bf16_f32 v166, v78, v79
	v_cvt_pk_bf16_f32 v167, v80, v81
	v_cvt_pk_bf16_f32 v168, v74, v75
	v_cvt_pk_bf16_f32 v169, v76, v77
	v_cvt_pk_bf16_f32 v170, v70, v71
	v_cvt_pk_bf16_f32 v171, v72, v73
	v_cvt_pk_bf16_f32 v172, v66, v67
	v_cvt_pk_bf16_f32 v173, v68, v69
	v_mul_f32_e32 v174, v78, v78
	v_mul_f32_e32 v175, v74, v74
	v_mul_f32_e32 v176, v70, v70
	v_mul_f32_e32 v177, v66, v66
	v_fmac_f32_e32 v174, v79, v79
	v_fmac_f32_e32 v175, v75, v75
	v_fmac_f32_e32 v176, v71, v71
	v_fmac_f32_e32 v177, v67, v67
	v_fmac_f32_e32 v174, v80, v80
	v_fmac_f32_e32 v175, v76, v76
	v_fmac_f32_e32 v176, v72, v72
	v_fmac_f32_e32 v177, v68, v68
	v_fmac_f32_e32 v174, v81, v81
	v_fmac_f32_e32 v175, v77, v77
	v_fmac_f32_e32 v176, v73, v73
	v_fmac_f32_e32 v177, v69, v69
	v_add_f32_e32 v174, v174, v175
	v_add_f32_e32 v176, v176, v177
	v_add_f32_e32 v178, v174, v176
	ds_bpermute_b32 v179, v131, v178
	v_permlane16_swap_b32_e32 v166, v168
	v_permlane16_swap_b32_e32 v167, v169
	v_permlane16_swap_b32_e32 v170, v172
	v_permlane16_swap_b32_e32 v171, v173
	v_add_u32_e32 v253, 0x18000, v252
	global_store_dwordx4 v253, v[166:169], s[14:15]
	global_store_dwordx4 v253, v[170:173], s[14:15] offset:256
	s_waitcnt lgkmcnt(0)
	v_add_f32_e32 v178, v178, v179
	ds_bpermute_b32 v179, v135, v178
	s_waitcnt lgkmcnt(0)
	v_add_f32_e32 v178, v178, v179
	s_and_saveexec_b64 s[30:31], s[8:9]
	global_store_dword v189, v178, s[16:17] offset:3072
	s_or_b64 exec, exec, s[30:31]
	s_waitcnt vmcnt(14)
; __device__ __forceinline__ float bf_lo(unsigned u) { return __uint_as_float(u << 16); }
; __device__ __forceinline__ float bf_hi(unsigned u) { return __uint_as_float(u & 0xffff0000u); }
; __device__ __forceinline__ unsigned pk_bf16(float lo, float hi) { const f32x2 v = {lo, hi}; const bf16x2_t b = __builtin_convertvector(v, bf16x2_t); return __builtin_bit_cast(unsigned, b); }
;     __device__ __forceinline__ void operator()(const f32x4 (&acc)[2][2][4][2], const pg8::Unit& u, int wr, int wc, int fr, int fq) const {
;     ...
;         for (int ai = 0; ai < 2; ++ai)
; #pragma unroll
;             for (int m = 0; m < 4; ++m) {
;                 const int row = row0 + ai * 128 + m * 16; const size_t off = (size_t)row * DM + col0; float q = 0.f;
;                 f32x4 r4[2][2];
;                 if (rf32) {
; #pragma unroll
;                     for (int bj = 0; bj < 2; ++bj)
; #pragma unroll
;                         for (int n = 0; n < 2; ++n) r4[bj][n] = *(const f32x4*)(rp + off + bj * 128 + n * 16);
;                 } else {
; #pragma unroll
;                     for (int bj = 0; bj < 2; ++bj)
; #pragma unroll
;                         for (int n = 0; n < 2; ++n) { const u32x2 w = *(const u32x2*)(XB + off + bj * 128 + n * 16); r4[bj][n] = (f32x4){bf_lo(w.x), bf_hi(w.x), bf_lo(w.y), bf_hi(w.y)}; }
;                 }
; #pragma unroll
;                 for (int bj = 0; bj < 2; ++bj)
; #pragma unroll
;                     for (int n = 0; n < 2; ++n) { const f32x4 x4 = r4[bj][n] + acc[ai][bj][m][n];
;                         q += (x4[0] * x4[0] + x4[1] * x4[1]) + (x4[2] * x4[2] + x4[3] * x4[3]);
;                         u32x2 w; w.x = pk_bf16(x4[0], x4[1]); w.y = pk_bf16(x4[2], x4[3]); *(u32x2*)(XB + off + bj * 128 + n * 16) = w; }
;                 q += __shfl_xor(q, 16); q += __shfl_xor(q, 32);
;                 if (fq == 0) ssq[(size_t)row * 16 + u.pn * 4 + wc] = q;
	v_permlane16_swap_b32_e32 v236, v238
	v_permlane16_swap_b32_e32 v237, v239
	v_permlane16_swap_b32_e32 v240, v242
	v_permlane16_swap_b32_e32 v241, v243
	v_lshlrev_b32_e32 v166, 16, v236
	v_and_b32_e32 v167, 0xffff0000, v236
	v_lshlrev_b32_e32 v168, 16, v237
	v_and_b32_e32 v169, 0xffff0000, v237
	v_lshlrev_b32_e32 v170, 16, v238
	v_and_b32_e32 v171, 0xffff0000, v238
	v_lshlrev_b32_e32 v172, 16, v239
	v_and_b32_e32 v173, 0xffff0000, v239
	v_lshlrev_b32_e32 v174, 16, v240
	v_and_b32_e32 v175, 0xffff0000, v240
	v_lshlrev_b32_e32 v176, 16, v241
	v_and_b32_e32 v177, 0xffff0000, v241
	v_lshlrev_b32_e32 v178, 16, v242
	v_and_b32_e32 v179, 0xffff0000, v242
	v_lshlrev_b32_e32 v180, 16, v243
	v_and_b32_e32 v181, 0xffff0000, v243
	v_pk_add_f32 v[62:63], v[62:63], v[166:167]
	v_pk_add_f32 v[64:65], v[64:65], v[168:169]
	v_pk_add_f32 v[58:59], v[58:59], v[170:171]
	v_pk_add_f32 v[60:61], v[60:61], v[172:173]
	v_pk_add_f32 v[54:55], v[54:55], v[174:175]
	v_pk_add_f32 v[56:57], v[56:57], v[176:177]
	v_pk_add_f32 v[50:51], v[50:51], v[178:179]
	v_pk_add_f32 v[52:53], v[52:53], v[180:181]
	v_cvt_pk_bf16_f32 v166, v62, v63
	v_cvt_pk_bf16_f32 v167, v64, v65
	v_cvt_pk_bf16_f32 v168, v58, v59
	v_cvt_pk_bf16_f32 v169, v60, v61
	v_cvt_pk_bf16_f32 v170, v54, v55
	v_cvt_pk_bf16_f32 v171, v56, v57
	v_cvt_pk_bf16_f32 v172, v50, v51
	v_cvt_pk_bf16_f32 v173, v52, v53
	v_mul_f32_e32 v174, v62, v62
	v_mul_f32_e32 v175, v58, v58
	v_mul_f32_e32 v176, v54, v54
	v_mul_f32_e32 v177, v50, v50
	v_fmac_f32_e32 v174, v63, v63
	v_fmac_f32_e32 v175, v59, v59
	v_fmac_f32_e32 v176, v55, v55
	v_fmac_f32_e32 v177, v51, v51
	v_fmac_f32_e32 v174, v64, v64
	v_fmac_f32_e32 v175, v60, v60
	v_fmac_f32_e32 v176, v56, v56
	v_fmac_f32_e32 v177, v52, v52
	v_fmac_f32_e32 v174, v65, v65
	v_fmac_f32_e32 v175, v61, v61
	v_fmac_f32_e32 v176, v57, v57
	v_fmac_f32_e32 v177, v53, v53
	v_add_f32_e32 v174, v174, v175
	v_add_f32_e32 v176, v176, v177
	v_add_f32_e32 v178, v174, v176
	ds_bpermute_b32 v179, v131, v178
	v_permlane16_swap_b32_e32 v166, v168
	v_permlane16_swap_b32_e32 v167, v169
	v_permlane16_swap_b32_e32 v170, v172
	v_permlane16_swap_b32_e32 v171, v173
	v_add_u32_e32 v253, 0x40000, v252
	global_store_dwordx4 v253, v[166:169], s[14:15]
	global_store_dwordx4 v253, v[170:173], s[14:15] offset:256
	s_waitcnt lgkmcnt(0)
	v_add_f32_e32 v178, v178, v179
	ds_bpermute_b32 v179, v135, v178
	v_add_u32_e32 v189, 0x2000, v189
	s_waitcnt lgkmcnt(0)
	v_add_f32_e32 v178, v178, v179
	s_and_saveexec_b64 s[30:31], s[8:9]
	global_store_dword v189, v178, s[16:17]
	s_or_b64 exec, exec, s[30:31]
	s_waitcnt vmcnt(14)
	v_permlane16_swap_b32_e32 v244, v246
	v_permlane16_swap_b32_e32 v245, v247
	v_permlane16_swap_b32_e32 v248, v250
	v_permlane16_swap_b32_e32 v249, v251
	v_lshlrev_b32_e32 v166, 16, v244
	v_and_b32_e32 v167, 0xffff0000, v244
	v_lshlrev_b32_e32 v168, 16, v245
	v_and_b32_e32 v169, 0xffff0000, v245
	v_lshlrev_b32_e32 v170, 16, v246
	v_and_b32_e32 v171, 0xffff0000, v246
	v_lshlrev_b32_e32 v172, 16, v247
	v_and_b32_e32 v173, 0xffff0000, v247
	v_lshlrev_b32_e32 v174, 16, v248
	v_and_b32_e32 v175, 0xffff0000, v248
	v_lshlrev_b32_e32 v176, 16, v249
	v_and_b32_e32 v177, 0xffff0000, v249
	v_lshlrev_b32_e32 v178, 16, v250
	v_and_b32_e32 v179, 0xffff0000, v250
	v_lshlrev_b32_e32 v180, 16, v251
	v_and_b32_e32 v181, 0xffff0000, v251
	v_pk_add_f32 v[46:47], v[46:47], v[166:167]
	v_pk_add_f32 v[48:49], v[48:49], v[168:169]
	v_pk_add_f32 v[42:43], v[42:43], v[170:171]
	v_pk_add_f32 v[44:45], v[44:45], v[172:173]
	v_pk_add_f32 v[38:39], v[38:39], v[174:175]
	v_pk_add_f32 v[40:41], v[40:41], v[176:177]
	v_pk_add_f32 v[34:35], v[34:35], v[178:179]
	v_pk_add_f32 v[36:37], v[36:37], v[180:181]
	v_cvt_pk_bf16_f32 v166, v46, v47
	v_cvt_pk_bf16_f32 v167, v48, v49
	v_cvt_pk_bf16_f32 v168, v42, v43
	v_cvt_pk_bf16_f32 v169, v44, v45
	v_cvt_pk_bf16_f32 v170, v38, v39
	v_cvt_pk_bf16_f32 v171, v40, v41
	v_cvt_pk_bf16_f32 v172, v34, v35
	v_cvt_pk_bf16_f32 v173, v36, v37
	v_mul_f32_e32 v174, v46, v46
	v_mul_f32_e32 v175, v42, v42
	v_mul_f32_e32 v176, v38, v38
	v_mul_f32_e32 v177, v34, v34
	v_fmac_f32_e32 v174, v47, v47
	v_fmac_f32_e32 v175, v43, v43
	v_fmac_f32_e32 v176, v39, v39
	v_fmac_f32_e32 v177, v35, v35
	v_fmac_f32_e32 v174, v48, v48
	v_fmac_f32_e32 v175, v44, v44
	v_fmac_f32_e32 v176, v40, v40
	v_fmac_f32_e32 v177, v36, v36
	v_fmac_f32_e32 v174, v49, v49
	v_fmac_f32_e32 v175, v45, v45
	v_fmac_f32_e32 v176, v41, v41
	v_fmac_f32_e32 v177, v37, v37
	v_add_f32_e32 v174, v174, v175
	v_add_f32_e32 v176, v176, v177
	v_add_f32_e32 v178, v174, v176
	ds_bpermute_b32 v179, v131, v178
	v_permlane16_swap_b32_e32 v166, v168
	v_permlane16_swap_b32_e32 v167, v169
	v_permlane16_swap_b32_e32 v170, v172
	v_permlane16_swap_b32_e32 v171, v173
	v_add_u32_e32 v253, 0x48000, v252
	global_store_dwordx4 v253, v[166:169], s[14:15]
	global_store_dwordx4 v253, v[170:173], s[14:15] offset:256
	s_waitcnt lgkmcnt(0)
	v_add_f32_e32 v178, v178, v179
	ds_bpermute_b32 v179, v135, v178
	s_waitcnt lgkmcnt(0)
	v_add_f32_e32 v178, v178, v179
	s_and_saveexec_b64 s[30:31], s[8:9]
	global_store_dword v189, v178, s[16:17] offset:1024
	s_or_b64 exec, exec, s[30:31]
	s_waitcnt vmcnt(14)
; __device__ __forceinline__ float bf_lo(unsigned u) { return __uint_as_float(u << 16); }
; __device__ __forceinline__ float bf_hi(unsigned u) { return __uint_as_float(u & 0xffff0000u); }
; __device__ __forceinline__ unsigned pk_bf16(float lo, float hi) { const f32x2 v = {lo, hi}; const bf16x2_t b = __builtin_convertvector(v, bf16x2_t); return __builtin_bit_cast(unsigned, b); }
;     __device__ __forceinline__ void operator()(const f32x4 (&acc)[2][2][4][2], const pg8::Unit& u, int wr, int wc, int fr, int fq) const {
;     ...
;         for (int ai = 0; ai < 2; ++ai)
; #pragma unroll
;             for (int m = 0; m < 4; ++m) {
;                 const int row = row0 + ai * 128 + m * 16; const size_t off = (size_t)row * DM + col0; float q = 0.f;
;                 f32x4 r4[2][2];
;                 if (rf32) {
; #pragma unroll
;                     for (int bj = 0; bj < 2; ++bj)
; #pragma unroll
;                         for (int n = 0; n < 2; ++n) r4[bj][n] = *(const f32x4*)(rp + off + bj * 128 + n * 16);
;                 } else {
; #pragma unroll
;                     for (int bj = 0; bj < 2; ++bj)
; #pragma unroll
;                         for (int n = 0; n < 2; ++n) { const u32x2 w = *(const u32x2*)(XB + off + bj * 128 + n * 16); r4[bj][n] = (f32x4){bf_lo(w.x), bf_hi(w.x), bf_lo(w.y), bf_hi(w.y)}; }
;                 }
; #pragma unroll
;                 for (int bj = 0; bj < 2; ++bj)
; #pragma unroll
;                     for (int n = 0; n < 2; ++n) { const f32x4 x4 = r4[bj][n] + acc[ai][bj][m][n];
;                         q += (x4[0] * x4[0] + x4[1] * x4[1]) + (x4[2] * x4[2] + x4[3] * x4[3]);
;                         u32x2 w; w.x = pk_bf16(x4[0], x4[1]); w.y = pk_bf16(x4[2], x4[3]); *(u32x2*)(XB + off + bj * 128 + n * 16) = w; }
;                 q += __shfl_xor(q, 16); q += __shfl_xor(q, 32);
;                 if (fq == 0) ssq[(size_t)row * 16 + u.pn * 4 + wc] = q;
;                 if (m & 1) asm volatile("" ::: "memory");
;             }
	v_permlane16_swap_b32_e32 v204, v206
	v_permlane16_swap_b32_e32 v205, v207
	v_permlane16_swap_b32_e32 v208, v210
	v_permlane16_swap_b32_e32 v209, v211
	v_lshlrev_b32_e32 v166, 16, v204
	v_and_b32_e32 v167, 0xffff0000, v204
	v_lshlrev_b32_e32 v168, 16, v205
	v_and_b32_e32 v169, 0xffff0000, v205
	v_lshlrev_b32_e32 v170, 16, v206
	v_and_b32_e32 v171, 0xffff0000, v206
	v_lshlrev_b32_e32 v172, 16, v207
	v_and_b32_e32 v173, 0xffff0000, v207
	v_lshlrev_b32_e32 v174, 16, v208
	v_and_b32_e32 v175, 0xffff0000, v208
	v_lshlrev_b32_e32 v176, 16, v209
	v_and_b32_e32 v177, 0xffff0000, v209
	v_lshlrev_b32_e32 v178, 16, v210
	v_and_b32_e32 v179, 0xffff0000, v210
	v_lshlrev_b32_e32 v180, 16, v211
	v_and_b32_e32 v181, 0xffff0000, v211
	v_pk_add_f32 v[30:31], v[30:31], v[166:167]
	v_pk_add_f32 v[32:33], v[32:33], v[168:169]
	v_pk_add_f32 v[26:27], v[26:27], v[170:171]
	v_pk_add_f32 v[28:29], v[28:29], v[172:173]
	v_pk_add_f32 v[22:23], v[22:23], v[174:175]
	v_pk_add_f32 v[24:25], v[24:25], v[176:177]
	v_pk_add_f32 v[18:19], v[18:19], v[178:179]
	v_pk_add_f32 v[20:21], v[20:21], v[180:181]
	v_cvt_pk_bf16_f32 v166, v30, v31
	v_cvt_pk_bf16_f32 v167, v32, v33
	v_cvt_pk_bf16_f32 v168, v26, v27
	v_cvt_pk_bf16_f32 v169, v28, v29
	v_cvt_pk_bf16_f32 v170, v22, v23
	v_cvt_pk_bf16_f32 v171, v24, v25
	v_cvt_pk_bf16_f32 v172, v18, v19
	v_cvt_pk_bf16_f32 v173, v20, v21
	v_mul_f32_e32 v174, v30, v30
	v_mul_f32_e32 v175, v26, v26
	v_mul_f32_e32 v176, v22, v22
	v_mul_f32_e32 v177, v18, v18
	v_fmac_f32_e32 v174, v31, v31
	v_fmac_f32_e32 v175, v27, v27
	v_fmac_f32_e32 v176, v23, v23
	v_fmac_f32_e32 v177, v19, v19
	v_fmac_f32_e32 v174, v32, v32
	v_fmac_f32_e32 v175, v28, v28
	v_fmac_f32_e32 v176, v24, v24
	v_fmac_f32_e32 v177, v20, v20
	v_fmac_f32_e32 v174, v33, v33
	v_fmac_f32_e32 v175, v29, v29
	v_fmac_f32_e32 v176, v25, v25
	v_fmac_f32_e32 v177, v21, v21
	v_add_f32_e32 v174, v174, v175
	v_add_f32_e32 v176, v176, v177
	v_add_f32_e32 v178, v174, v176
	ds_bpermute_b32 v179, v131, v178
	v_permlane16_swap_b32_e32 v166, v168
	v_permlane16_swap_b32_e32 v167, v169
	v_permlane16_swap_b32_e32 v170, v172
	v_permlane16_swap_b32_e32 v171, v173
	v_add_u32_e32 v253, 0x50000, v252
	global_store_dwordx4 v253, v[166:169], s[14:15]
	global_store_dwordx4 v253, v[170:173], s[14:15] offset:256
	s_waitcnt lgkmcnt(0)
	v_add_f32_e32 v178, v178, v179
	ds_bpermute_b32 v179, v135, v178
	s_waitcnt lgkmcnt(0)
	v_add_f32_e32 v178, v178, v179
	s_and_saveexec_b64 s[30:31], s[8:9]
	global_store_dword v189, v178, s[16:17] offset:2048
	s_or_b64 exec, exec, s[30:31]
	s_waitcnt vmcnt(12)
	v_permlane16_swap_b32_e32 v212, v214
	v_permlane16_swap_b32_e32 v213, v215
	v_permlane16_swap_b32_e32 v216, v218
	v_permlane16_swap_b32_e32 v217, v219
	v_lshlrev_b32_e32 v166, 16, v212
	v_and_b32_e32 v167, 0xffff0000, v212
	v_lshlrev_b32_e32 v168, 16, v213
	v_and_b32_e32 v169, 0xffff0000, v213
	v_lshlrev_b32_e32 v170, 16, v214
	v_and_b32_e32 v171, 0xffff0000, v214
	v_lshlrev_b32_e32 v172, 16, v215
	v_and_b32_e32 v173, 0xffff0000, v215
	v_lshlrev_b32_e32 v174, 16, v216
	v_and_b32_e32 v175, 0xffff0000, v216
	v_lshlrev_b32_e32 v176, 16, v217
	v_and_b32_e32 v177, 0xffff0000, v217
	v_lshlrev_b32_e32 v178, 16, v218
	v_and_b32_e32 v179, 0xffff0000, v218
	v_lshlrev_b32_e32 v180, 16, v219
	v_and_b32_e32 v181, 0xffff0000, v219
	v_pk_add_f32 v[14:15], v[14:15], v[166:167]
	v_pk_add_f32 v[16:17], v[16:17], v[168:169]
	v_pk_add_f32 v[10:11], v[10:11], v[170:171]
	v_pk_add_f32 v[12:13], v[12:13], v[172:173]
	v_pk_add_f32 v[6:7], v[6:7], v[174:175]
	v_pk_add_f32 v[8:9], v[8:9], v[176:177]
	v_pk_add_f32 v[2:3], v[2:3], v[178:179]
	v_pk_add_f32 v[4:5], v[4:5], v[180:181]
	v_cvt_pk_bf16_f32 v166, v14, v15
	v_cvt_pk_bf16_f32 v167, v16, v17
	v_cvt_pk_bf16_f32 v168, v10, v11
	v_cvt_pk_bf16_f32 v169, v12, v13
	v_cvt_pk_bf16_f32 v170, v6, v7
	v_cvt_pk_bf16_f32 v171, v8, v9
	v_cvt_pk_bf16_f32 v172, v2, v3
	v_cvt_pk_bf16_f32 v173, v4, v5
	v_mul_f32_e32 v174, v14, v14
	v_mul_f32_e32 v175, v10, v10
	v_mul_f32_e32 v176, v6, v6
	v_mul_f32_e32 v177, v2, v2
	v_fmac_f32_e32 v174, v15, v15
	v_fmac_f32_e32 v175, v11, v11
	v_fmac_f32_e32 v176, v7, v7
	v_fmac_f32_e32 v177, v3, v3
	v_fmac_f32_e32 v174, v16, v16
	v_fmac_f32_e32 v175, v12, v12
	v_fmac_f32_e32 v176, v8, v8
	v_fmac_f32_e32 v177, v4, v4
	v_fmac_f32_e32 v174, v17, v17
	v_fmac_f32_e32 v175, v13, v13
	v_fmac_f32_e32 v176, v9, v9
	v_fmac_f32_e32 v177, v5, v5
	v_add_f32_e32 v174, v174, v175
	v_add_f32_e32 v176, v176, v177
	v_add_f32_e32 v178, v174, v176
	ds_bpermute_b32 v179, v131, v178
	v_permlane16_swap_b32_e32 v166, v168
	v_permlane16_swap_b32_e32 v167, v169
	v_permlane16_swap_b32_e32 v170, v172
	v_permlane16_swap_b32_e32 v171, v173
	v_add_u32_e32 v253, 0x58000, v252
	global_store_dwordx4 v253, v[166:169], s[14:15]
	global_store_dwordx4 v253, v[170:173], s[14:15] offset:256
	s_waitcnt lgkmcnt(0)
	v_add_f32_e32 v178, v178, v179
	ds_bpermute_b32 v179, v135, v178
	s_waitcnt lgkmcnt(0)
	v_add_f32_e32 v178, v178, v179
	s_and_saveexec_b64 s[30:31], s[8:9]
	global_store_dword v189, v178, s[16:17] offset:3072
	s_or_b64 exec, exec, s[30:31]
.LBB0_1699:
	s_andn2_b64 vcc, exec, s[10:11]
	s_mov_b64 s[10:11], -1
	s_cbranch_vccnz .LBB0_1672
	s_andn2_b64 vcc, exec, s[12:13]
	s_cbranch_vccnz .LBB0_1671
	s_barrier
	s_branch .LBB0_1671

; __device__ __forceinline__ float bf_lo(unsigned u) { return __uint_as_float(u << 16); }
; __device__ __forceinline__ float bf_hi(unsigned u) { return __uint_as_float(u & 0xffff0000u); }
; __device__ __forceinline__ unsigned pk_bf16(float lo, float hi) { const f32x2 v = {lo, hi}; const bf16x2_t b = __builtin_convertvector(v, bf16x2_t); return __builtin_bit_cast(unsigned, b); }
;     __device__ __forceinline__ void operator()(const f32x4 (&acc)[2][2][4][2], const pg8::Unit& u, int wr, int wc, int fr, int fq) const {
;         asm volatile("" : "+v"(fr));
;         const int row0 = u.pm * 256 + wr * 64 + fr, col0 = u.pn * 256 + wc * 32 + 4 * fq;
;         const bool rf32 = (rp != nullptr) && (u.pm < MP / 256);
; #pragma unroll
;         for (int ai = 0; ai < 2; ++ai)
; #pragma unroll
;             for (int m = 0; m < 4; ++m) {
;                 const int row = row0 + ai * 128 + m * 16; const size_t off = (size_t)row * DM + col0; float q = 0.f;
;                 f32x4 r4[2][2];
;                 if (rf32) {
; #pragma unroll
;                     for (int bj = 0; bj < 2; ++bj)
; #pragma unroll
;                         for (int n = 0; n < 2; ++n) r4[bj][n] = *(const f32x4*)(rp + off + bj * 128 + n * 16);
;                 } else {
; #pragma unroll
;                     for (int bj = 0; bj < 2; ++bj)
; #pragma unroll
;                         for (int n = 0; n < 2; ++n) { const u32x2 w = *(const u32x2*)(XB + off + bj * 128 + n * 16); r4[bj][n] = (f32x4){bf_lo(w.x), bf_hi(w.x), bf_lo(w.y), bf_hi(w.y)}; }
;                 }
; #pragma unroll
;                 for (int bj = 0; bj < 2; ++bj)
; #pragma unroll
;                     for (int n = 0; n < 2; ++n) { const f32x4 x4 = r4[bj][n] + acc[ai][bj][m][n];
;                         q += (x4[0] * x4[0] + x4[1] * x4[1]) + (x4[2] * x4[2] + x4[3] * x4[3]);
;                         u32x2 w; w.x = pk_bf16(x4[0], x4[1]); w.y = pk_bf16(x4[2], x4[3]); *(u32x2*)(XB + off + bj * 128 + n * 16) = w; }
;                 q += __shfl_xor(q, 16); q += __shfl_xor(q, 32);
;                 if (fq == 0) ssq[(size_t)row * 16 + u.pn * 4 + wc] = q;
.LBB0_1893:
	s_lshl_b32 s4, s47, 8
	v_mov_b32_e32 v158, v1
	s_add_i32 s4, s4, s40
	s_lshl_b32 s22, s46, 2
	v_add_u32_e32 v160, s4, v158
	v_ashrrev_i32_e32 v161, 31, v160
	v_lshl_or_b32 v158, s46, 8, v163
	v_lshlrev_b64 v[166:167], 11, v[160:161]
	v_ashrrev_i32_e32 v159, 31, v158
	v_lshl_add_u64 v[166:167], s[14:15], 0, v[166:167]
	v_lshl_add_u64 v[166:167], v[158:159], 1, v[166:167]
	s_ashr_i32 s23, s22, 31
	v_lshlrev_b32_e32 v252, 11, v160
	v_lshl_add_u32 v252, v158, 1, v252
	v_bfe_u32 v253, v190, 4, 1
	v_mul_u32_u24_e32 v253, 24, v253
	v_add_u32_e32 v252, v252, v253
	s_lshl_b32 s88, s39, 2
	v_lshl_add_u32 v189, v160, 6, s88
	v_lshl_add_u32 v189, s22, 2, v189
	global_load_dwordx4 v[204:207], v252, s[14:15]
	global_load_dwordx4 v[208:211], v252, s[14:15] offset:256
	v_add_u32_e32 v253, 0x8000, v252
	global_load_dwordx4 v[212:215], v253, s[14:15]
	global_load_dwordx4 v[216:219], v253, s[14:15] offset:256
	v_add_u32_e32 v253, 0x10000, v252
	global_load_dwordx4 v[220:223], v253, s[14:15]
	global_load_dwordx4 v[224:227], v253, s[14:15] offset:256
	v_add_u32_e32 v253, 0x18000, v252
	global_load_dwordx4 v[228:231], v253, s[14:15]
	global_load_dwordx4 v[232:235], v253, s[14:15] offset:256
	v_add_u32_e32 v253, 0x40000, v252
	global_load_dwordx4 v[236:239], v253, s[14:15]
	global_load_dwordx4 v[240:243], v253, s[14:15] offset:256
	v_add_u32_e32 v253, 0x48000, v252
	global_load_dwordx4 v[244:247], v253, s[14:15]
	global_load_dwordx4 v[248:251], v253, s[14:15] offset:256
	s_waitcnt vmcnt(10)
	v_permlane16_swap_b32_e32 v204, v206
	v_permlane16_swap_b32_e32 v205, v207
	v_permlane16_swap_b32_e32 v208, v210
	v_permlane16_swap_b32_e32 v209, v211
	v_lshlrev_b32_e32 v166, 16, v204
	v_and_b32_e32 v167, 0xffff0000, v204
	v_lshlrev_b32_e32 v168, 16, v205
	v_and_b32_e32 v169, 0xffff0000, v205
	v_lshlrev_b32_e32 v170, 16, v206
	v_and_b32_e32 v171, 0xffff0000, v206
	v_lshlrev_b32_e32 v172, 16, v207
	v_and_b32_e32 v173, 0xffff0000, v207
	v_lshlrev_b32_e32 v174, 16, v208
	v_and_b32_e32 v175, 0xffff0000, v208
	v_lshlrev_b32_e32 v176, 16, v209
	v_and_b32_e32 v177, 0xffff0000, v209
	v_lshlrev_b32_e32 v178, 16, v210
	v_and_b32_e32 v179, 0xffff0000, v210
	v_lshlrev_b32_e32 v180, 16, v211
	v_and_b32_e32 v181, 0xffff0000, v211
	v_pk_add_f32 v[126:127], v[126:127], v[166:167]
	v_pk_add_f32 v[128:129], v[128:129], v[168:169]
	v_pk_add_f32 v[122:123], v[122:123], v[170:171]
	v_pk_add_f32 v[124:125], v[124:125], v[172:173]
	v_pk_add_f32 v[118:119], v[118:119], v[174:175]
	v_pk_add_f32 v[120:121], v[120:121], v[176:177]
	v_pk_add_f32 v[114:115], v[114:115], v[178:179]
	v_pk_add_f32 v[116:117], v[116:117], v[180:181]
	v_add_u32_e32 v253, 0x50000, v252
	global_load_dwordx4 v[204:207], v253, s[14:15]
	global_load_dwordx4 v[208:211], v253, s[14:15] offset:256
	v_cvt_pk_bf16_f32 v166, v126, v127
	v_cvt_pk_bf16_f32 v167, v128, v129
	v_cvt_pk_bf16_f32 v168, v122, v123
	v_cvt_pk_bf16_f32 v169, v124, v125
	v_cvt_pk_bf16_f32 v170, v118, v119
	v_cvt_pk_bf16_f32 v171, v120, v121
	v_cvt_pk_bf16_f32 v172, v114, v115
	v_cvt_pk_bf16_f32 v173, v116, v117
	v_mul_f32_e32 v174, v126, v126
	v_mul_f32_e32 v175, v122, v122
	v_mul_f32_e32 v176, v118, v118
	v_mul_f32_e32 v177, v114, v114
	v_fmac_f32_e32 v174, v127, v127
	v_fmac_f32_e32 v175, v123, v123
	v_fmac_f32_e32 v176, v119, v119
	v_fmac_f32_e32 v177, v115, v115
	v_fmac_f32_e32 v174, v128, v128
	v_fmac_f32_e32 v175, v124, v124
	v_fmac_f32_e32 v176, v120, v120
	v_fmac_f32_e32 v177, v116, v116
	v_fmac_f32_e32 v174, v129, v129
	v_fmac_f32_e32 v175, v125, v125
	v_fmac_f32_e32 v176, v121, v121
	v_fmac_f32_e32 v177, v117, v117
	v_add_f32_e32 v174, v174, v175
	v_add_f32_e32 v176, v176, v177
	v_add_f32_e32 v178, v174, v176
	ds_bpermute_b32 v179, v131, v178
	v_permlane16_swap_b32_e32 v166, v168
	v_permlane16_swap_b32_e32 v167, v169
	v_permlane16_swap_b32_e32 v170, v172
	v_permlane16_swap_b32_e32 v171, v173
	global_store_dwordx4 v252, v[166:169], s[14:15]
	global_store_dwordx4 v252, v[170:173], s[14:15] offset:256
	s_waitcnt lgkmcnt(0)
	v_add_f32_e32 v178, v178, v179
	ds_bpermute_b32 v179, v135, v178
	s_waitcnt lgkmcnt(0)
	v_add_f32_e32 v178, v178, v179
	s_and_saveexec_b64 s[24:25], s[6:7]
	global_store_dword v189, v178, s[16:17]
	s_or_b64 exec, exec, s[24:25]
	s_waitcnt vmcnt(12)
	v_permlane16_swap_b32_e32 v212, v214
	v_permlane16_swap_b32_e32 v213, v215
	v_permlane16_swap_b32_e32 v216, v218
	v_permlane16_swap_b32_e32 v217, v219
	v_lshlrev_b32_e32 v166, 16, v212
	v_and_b32_e32 v167, 0xffff0000, v212
	v_lshlrev_b32_e32 v168, 16, v213
	v_and_b32_e32 v169, 0xffff0000, v213
	v_lshlrev_b32_e32 v170, 16, v214
	v_and_b32_e32 v171, 0xffff0000, v214
	v_lshlrev_b32_e32 v172, 16, v215
	v_and_b32_e32 v173, 0xffff0000, v215
	v_lshlrev_b32_e32 v174, 16, v216
	v_and_b32_e32 v175, 0xffff0000, v216
	v_lshlrev_b32_e32 v176, 16, v217
	v_and_b32_e32 v177, 0xffff0000, v217
	v_lshlrev_b32_e32 v178, 16, v218
	v_and_b32_e32 v179, 0xffff0000, v218
	v_lshlrev_b32_e32 v180, 16, v219
	v_and_b32_e32 v181, 0xffff0000, v219
	v_pk_add_f32 v[110:111], v[110:111], v[166:167]
	v_pk_add_f32 v[112:113], v[112:113], v[168:169]
	v_pk_add_f32 v[106:107], v[106:107], v[170:171]
	v_pk_add_f32 v[108:109], v[108:109], v[172:173]
	v_pk_add_f32 v[102:103], v[102:103], v[174:175]
	v_pk_add_f32 v[104:105], v[104:105], v[176:177]
	v_pk_add_f32 v[98:99], v[98:99], v[178:179]
	v_pk_add_f32 v[100:101], v[100:101], v[180:181]
	v_add_u32_e32 v253, 0x58000, v252
	global_load_dwordx4 v[212:215], v253, s[14:15]
	global_load_dwordx4 v[216:219], v253, s[14:15] offset:256
	v_cvt_pk_bf16_f32 v166, v110, v111
	v_cvt_pk_bf16_f32 v167, v112, v113
	v_cvt_pk_bf16_f32 v168, v106, v107
	v_cvt_pk_bf16_f32 v169, v108, v109
	v_cvt_pk_bf16_f32 v170, v102, v103
	v_cvt_pk_bf16_f32 v171, v104, v105
	v_cvt_pk_bf16_f32 v172, v98, v99
	v_cvt_pk_bf16_f32 v173, v100, v101
	v_mul_f32_e32 v174, v110, v110
	v_mul_f32_e32 v175, v106, v106
	v_mul_f32_e32 v176, v102, v102
	v_mul_f32_e32 v177, v98, v98
	v_fmac_f32_e32 v174, v111, v111
	v_fmac_f32_e32 v175, v107, v107
	v_fmac_f32_e32 v176, v103, v103
	v_fmac_f32_e32 v177, v99, v99
	v_fmac_f32_e32 v174, v112, v112
	v_fmac_f32_e32 v175, v108, v108
	v_fmac_f32_e32 v176, v104, v104
	v_fmac_f32_e32 v177, v100, v100
	v_fmac_f32_e32 v174, v113, v113
	v_fmac_f32_e32 v175, v109, v109
	v_fmac_f32_e32 v176, v105, v105
	v_fmac_f32_e32 v177, v101, v101
	v_add_f32_e32 v174, v174, v175
	v_add_f32_e32 v176, v176, v177
	v_add_f32_e32 v178, v174, v176
	ds_bpermute_b32 v179, v131, v178
	v_permlane16_swap_b32_e32 v166, v168
	v_permlane16_swap_b32_e32 v167, v169
	v_permlane16_swap_b32_e32 v170, v172
	v_permlane16_swap_b32_e32 v171, v173
	v_add_u32_e32 v253, 0x8000, v252
	global_store_dwordx4 v253, v[166:169], s[14:15]
	global_store_dwordx4 v253, v[170:173], s[14:15] offset:256
	s_waitcnt lgkmcnt(0)
; __device__ __forceinline__ float bf_lo(unsigned u) { return __uint_as_float(u << 16); }
; __device__ __forceinline__ float bf_hi(unsigned u) { return __uint_as_float(u & 0xffff0000u); }
; __device__ __forceinline__ unsigned pk_bf16(float lo, float hi) { const f32x2 v = {lo, hi}; const bf16x2_t b = __builtin_convertvector(v, bf16x2_t); return __builtin_bit_cast(unsigned, b); }
;     __device__ __forceinline__ void operator()(const f32x4 (&acc)[2][2][4][2], const pg8::Unit& u, int wr, int wc, int fr, int fq) const {
;     ...
;         for (int ai = 0; ai < 2; ++ai)
; #pragma unroll
;             for (int m = 0; m < 4; ++m) {
;                 const int row = row0 + ai * 128 + m * 16; const size_t off = (size_t)row * DM + col0; float q = 0.f;
;                 f32x4 r4[2][2];
;                 if (rf32) {
; #pragma unroll
;                     for (int bj = 0; bj < 2; ++bj)
; #pragma unroll
;                         for (int n = 0; n < 2; ++n) r4[bj][n] = *(const f32x4*)(rp + off + bj * 128 + n * 16);
;                 } else {
; #pragma unroll
;                     for (int bj = 0; bj < 2; ++bj)
; #pragma unroll
;                         for (int n = 0; n < 2; ++n) { const u32x2 w = *(const u32x2*)(XB + off + bj * 128 + n * 16); r4[bj][n] = (f32x4){bf_lo(w.x), bf_hi(w.x), bf_lo(w.y), bf_hi(w.y)}; }
;                 }
; #pragma unroll
;                 for (int bj = 0; bj < 2; ++bj)
; #pragma unroll
;                     for (int n = 0; n < 2; ++n) { const f32x4 x4 = r4[bj][n] + acc[ai][bj][m][n];
;                         q += (x4[0] * x4[0] + x4[1] * x4[1]) + (x4[2] * x4[2] + x4[3] * x4[3]);
;                         u32x2 w; w.x = pk_bf16(x4[0], x4[1]); w.y = pk_bf16(x4[2], x4[3]); *(u32x2*)(XB + off + bj * 128 + n * 16) = w; }
;                 q += __shfl_xor(q, 16); q += __shfl_xor(q, 32);
;                 if (fq == 0) ssq[(size_t)row * 16 + u.pn * 4 + wc] = q;
	v_add_f32_e32 v178, v178, v179
	ds_bpermute_b32 v179, v135, v178
	s_waitcnt lgkmcnt(0)
	v_add_f32_e32 v178, v178, v179
	s_and_saveexec_b64 s[24:25], s[6:7]
	global_store_dword v189, v178, s[16:17] offset:1024
	s_or_b64 exec, exec, s[24:25]
	s_waitcnt vmcnt(14)
	v_permlane16_swap_b32_e32 v220, v222
	v_permlane16_swap_b32_e32 v221, v223
	v_permlane16_swap_b32_e32 v224, v226
	v_permlane16_swap_b32_e32 v225, v227
	v_lshlrev_b32_e32 v166, 16, v220
	v_and_b32_e32 v167, 0xffff0000, v220
	v_lshlrev_b32_e32 v168, 16, v221
	v_and_b32_e32 v169, 0xffff0000, v221
	v_lshlrev_b32_e32 v170, 16, v222
	v_and_b32_e32 v171, 0xffff0000, v222
	v_lshlrev_b32_e32 v172, 16, v223
	v_and_b32_e32 v173, 0xffff0000, v223
	v_lshlrev_b32_e32 v174, 16, v224
	v_and_b32_e32 v175, 0xffff0000, v224
	v_lshlrev_b32_e32 v176, 16, v225
	v_and_b32_e32 v177, 0xffff0000, v225
	v_lshlrev_b32_e32 v178, 16, v226
	v_and_b32_e32 v179, 0xffff0000, v226
	v_lshlrev_b32_e32 v180, 16, v227
	v_and_b32_e32 v181, 0xffff0000, v227
	v_pk_add_f32 v[94:95], v[94:95], v[166:167]
	v_pk_add_f32 v[96:97], v[96:97], v[168:169]
	v_pk_add_f32 v[90:91], v[90:91], v[170:171]
	v_pk_add_f32 v[92:93], v[92:93], v[172:173]
	v_pk_add_f32 v[86:87], v[86:87], v[174:175]
	v_pk_add_f32 v[88:89], v[88:89], v[176:177]
	v_pk_add_f32 v[82:83], v[82:83], v[178:179]
	v_pk_add_f32 v[84:85], v[84:85], v[180:181]
	v_cvt_pk_bf16_f32 v166, v94, v95
	v_cvt_pk_bf16_f32 v167, v96, v97
	v_cvt_pk_bf16_f32 v168, v90, v91
	v_cvt_pk_bf16_f32 v169, v92, v93
	v_cvt_pk_bf16_f32 v170, v86, v87
	v_cvt_pk_bf16_f32 v171, v88, v89
	v_cvt_pk_bf16_f32 v172, v82, v83
	v_cvt_pk_bf16_f32 v173, v84, v85
	v_mul_f32_e32 v174, v94, v94
	v_mul_f32_e32 v175, v90, v90
	v_mul_f32_e32 v176, v86, v86
	v_mul_f32_e32 v177, v82, v82
	v_fmac_f32_e32 v174, v95, v95
	v_fmac_f32_e32 v175, v91, v91
	v_fmac_f32_e32 v176, v87, v87
	v_fmac_f32_e32 v177, v83, v83
	v_fmac_f32_e32 v174, v96, v96
	v_fmac_f32_e32 v175, v92, v92
	v_fmac_f32_e32 v176, v88, v88
	v_fmac_f32_e32 v177, v84, v84
	v_fmac_f32_e32 v174, v97, v97
	v_fmac_f32_e32 v175, v93, v93
	v_fmac_f32_e32 v176, v89, v89
	v_fmac_f32_e32 v177, v85, v85
	v_add_f32_e32 v174, v174, v175
	v_add_f32_e32 v176, v176, v177
	v_add_f32_e32 v178, v174, v176
	ds_bpermute_b32 v179, v131, v178
	v_permlane16_swap_b32_e32 v166, v168
	v_permlane16_swap_b32_e32 v167, v169
	v_permlane16_swap_b32_e32 v170, v172
	v_permlane16_swap_b32_e32 v171, v173
	v_add_u32_e32 v253, 0x10000, v252
	global_store_dwordx4 v253, v[166:169], s[14:15]
	global_store_dwordx4 v253, v[170:173], s[14:15] offset:256
	s_waitcnt lgkmcnt(0)
	v_add_f32_e32 v178, v178, v179
	ds_bpermute_b32 v179, v135, v178
	s_waitcnt lgkmcnt(0)
	v_add_f32_e32 v178, v178, v179
	s_and_saveexec_b64 s[24:25], s[6:7]
	global_store_dword v189, v178, s[16:17] offset:2048
	s_or_b64 exec, exec, s[24:25]
	s_waitcnt vmcnt(14)
	v_permlane16_swap_b32_e32 v228, v230
	v_permlane16_swap_b32_e32 v229, v231
	v_permlane16_swap_b32_e32 v232, v234
	v_permlane16_swap_b32_e32 v233, v235
	v_lshlrev_b32_e32 v166, 16, v228
	v_and_b32_e32 v167, 0xffff0000, v228
	v_lshlrev_b32_e32 v168, 16, v229
	v_and_b32_e32 v169, 0xffff0000, v229
	v_lshlrev_b32_e32 v170, 16, v230
	v_and_b32_e32 v171, 0xffff0000, v230
	v_lshlrev_b32_e32 v172, 16, v231
	v_and_b32_e32 v173, 0xffff0000, v231
	v_lshlrev_b32_e32 v174, 16, v232
	v_and_b32_e32 v175, 0xffff0000, v232
	v_lshlrev_b32_e32 v176, 16, v233
	v_and_b32_e32 v177, 0xffff0000, v233
	v_lshlrev_b32_e32 v178, 16, v234
	v_and_b32_e32 v179, 0xffff0000, v234
	v_lshlrev_b32_e32 v180, 16, v235
	v_and_b32_e32 v181, 0xffff0000, v235
	v_pk_add_f32 v[78:79], v[78:79], v[166:167]
	v_pk_add_f32 v[80:81], v[80:81], v[168:169]
	v_pk_add_f32 v[74:75], v[74:75], v[170:171]
	v_pk_add_f32 v[76:77], v[76:77], v[172:173]
	v_pk_add_f32 v[70:71], v[70:71], v[174:175]
	v_pk_add_f32 v[72:73], v[72:73], v[176:177]
	v_pk_add_f32 v[66:67], v[66:67], v[178:179]
	v_pk_add_f32 v[68:69], v[68:69], v[180:181]
	v_cvt_pk_bf16_f32 v166, v78, v79
	v_cvt_pk_bf16_f32 v167, v80, v81
	v_cvt_pk_bf16_f32 v168, v74, v75
	v_cvt_pk_bf16_f32 v169, v76, v77
	v_cvt_pk_bf16_f32 v170, v70, v71
	v_cvt_pk_bf16_f32 v171, v72, v73
	v_cvt_pk_bf16_f32 v172, v66, v67
	v_cvt_pk_bf16_f32 v173, v68, v69
	v_mul_f32_e32 v174, v78, v78
	v_mul_f32_e32 v175, v74, v74
	v_mul_f32_e32 v176, v70, v70
	v_mul_f32_e32 v177, v66, v66
	v_fmac_f32_e32 v174, v79, v79
	v_fmac_f32_e32 v175, v75, v75
	v_fmac_f32_e32 v176, v71, v71
	v_fmac_f32_e32 v177, v67, v67
	v_fmac_f32_e32 v174, v80, v80
	v_fmac_f32_e32 v175, v76, v76
	v_fmac_f32_e32 v176, v72, v72
	v_fmac_f32_e32 v177, v68, v68
	v_fmac_f32_e32 v174, v81, v81
	v_fmac_f32_e32 v175, v77, v77
	v_fmac_f32_e32 v176, v73, v73
	v_fmac_f32_e32 v177, v69, v69
	v_add_f32_e32 v174, v174, v175
	v_add_f32_e32 v176, v176, v177
	v_add_f32_e32 v178, v174, v176
	ds_bpermute_b32 v179, v131, v178
	v_permlane16_swap_b32_e32 v166, v168
	v_permlane16_swap_b32_e32 v167, v169
	v_permlane16_swap_b32_e32 v170, v172
	v_permlane16_swap_b32_e32 v171, v173
	v_add_u32_e32 v253, 0x18000, v252
	global_store_dwordx4 v253, v[166:169], s[14:15]
	global_store_dwordx4 v253, v[170:173], s[14:15] offset:256
	s_waitcnt lgkmcnt(0)
	v_add_f32_e32 v178, v178, v179
	ds_bpermute_b32 v179, v135, v178
	s_waitcnt lgkmcnt(0)
	v_add_f32_e32 v178, v178, v179
	s_and_saveexec_b64 s[24:25], s[6:7]
	global_store_dword v189, v178, s[16:17] offset:3072
	s_or_b64 exec, exec, s[24:25]
	s_waitcnt vmcnt(14)
; __device__ __forceinline__ float bf_lo(unsigned u) { return __uint_as_float(u << 16); }
; __device__ __forceinline__ float bf_hi(unsigned u) { return __uint_as_float(u & 0xffff0000u); }
; __device__ __forceinline__ unsigned pk_bf16(float lo, float hi) { const f32x2 v = {lo, hi}; const bf16x2_t b = __builtin_convertvector(v, bf16x2_t); return __builtin_bit_cast(unsigned, b); }
;     __device__ __forceinline__ void operator()(const f32x4 (&acc)[2][2][4][2], const pg8::Unit& u, int wr, int wc, int fr, int fq) const {
;     ...
;         for (int ai = 0; ai < 2; ++ai)
; #pragma unroll
;             for (int m = 0; m < 4; ++m) {
;                 const int row = row0 + ai * 128 + m * 16; const size_t off = (size_t)row * DM + col0; float q = 0.f;
;                 f32x4 r4[2][2];
;                 if (rf32) {
; #pragma unroll
;                     for (int bj = 0; bj < 2; ++bj)
; #pragma unroll
;                         for (int n = 0; n < 2; ++n) r4[bj][n] = *(const f32x4*)(rp + off + bj * 128 + n * 16);
;                 } else {
; #pragma unroll
;                     for (int bj = 0; bj < 2; ++bj)
; #pragma unroll
;                         for (int n = 0; n < 2; ++n) { const u32x2 w = *(const u32x2*)(XB + off + bj * 128 + n * 16); r4[bj][n] = (f32x4){bf_lo(w.x), bf_hi(w.x), bf_lo(w.y), bf_hi(w.y)}; }
;                 }
; #pragma unroll
;                 for (int bj = 0; bj < 2; ++bj)
; #pragma unroll
;                     for (int n = 0; n < 2; ++n) { const f32x4 x4 = r4[bj][n] + acc[ai][bj][m][n];
;                         q += (x4[0] * x4[0] + x4[1] * x4[1]) + (x4[2] * x4[2] + x4[3] * x4[3]);
;                         u32x2 w; w.x = pk_bf16(x4[0], x4[1]); w.y = pk_bf16(x4[2], x4[3]); *(u32x2*)(XB + off + bj * 128 + n * 16) = w; }
;                 q += __shfl_xor(q, 16); q += __shfl_xor(q, 32);
;                 if (fq == 0) ssq[(size_t)row * 16 + u.pn * 4 + wc] = q;
	v_permlane16_swap_b32_e32 v236, v238
	v_permlane16_swap_b32_e32 v237, v239
	v_permlane16_swap_b32_e32 v240, v242
	v_permlane16_swap_b32_e32 v241, v243
	v_lshlrev_b32_e32 v166, 16, v236
	v_and_b32_e32 v167, 0xffff0000, v236
	v_lshlrev_b32_e32 v168, 16, v237
	v_and_b32_e32 v169, 0xffff0000, v237
	v_lshlrev_b32_e32 v170, 16, v238
	v_and_b32_e32 v171, 0xffff0000, v238
	v_lshlrev_b32_e32 v172, 16, v239
	v_and_b32_e32 v173, 0xffff0000, v239
	v_lshlrev_b32_e32 v174, 16, v240
	v_and_b32_e32 v175, 0xffff0000, v240
	v_lshlrev_b32_e32 v176, 16, v241
	v_and_b32_e32 v177, 0xffff0000, v241
	v_lshlrev_b32_e32 v178, 16, v242
	v_and_b32_e32 v179, 0xffff0000, v242
	v_lshlrev_b32_e32 v180, 16, v243
	v_and_b32_e32 v181, 0xffff0000, v243
	v_pk_add_f32 v[62:63], v[62:63], v[166:167]
	v_pk_add_f32 v[64:65], v[64:65], v[168:169]
	v_pk_add_f32 v[58:59], v[58:59], v[170:171]
	v_pk_add_f32 v[60:61], v[60:61], v[172:173]
	v_pk_add_f32 v[54:55], v[54:55], v[174:175]
	v_pk_add_f32 v[56:57], v[56:57], v[176:177]
	v_pk_add_f32 v[50:51], v[50:51], v[178:179]
	v_pk_add_f32 v[52:53], v[52:53], v[180:181]
	v_cvt_pk_bf16_f32 v166, v62, v63
	v_cvt_pk_bf16_f32 v167, v64, v65
	v_cvt_pk_bf16_f32 v168, v58, v59
	v_cvt_pk_bf16_f32 v169, v60, v61
	v_cvt_pk_bf16_f32 v170, v54, v55
	v_cvt_pk_bf16_f32 v171, v56, v57
	v_cvt_pk_bf16_f32 v172, v50, v51
	v_cvt_pk_bf16_f32 v173, v52, v53
	v_mul_f32_e32 v174, v62, v62
	v_mul_f32_e32 v175, v58, v58
	v_mul_f32_e32 v176, v54, v54
	v_mul_f32_e32 v177, v50, v50
	v_fmac_f32_e32 v174, v63, v63
	v_fmac_f32_e32 v175, v59, v59
	v_fmac_f32_e32 v176, v55, v55
	v_fmac_f32_e32 v177, v51, v51
	v_fmac_f32_e32 v174, v64, v64
	v_fmac_f32_e32 v175, v60, v60
	v_fmac_f32_e32 v176, v56, v56
	v_fmac_f32_e32 v177, v52, v52
	v_fmac_f32_e32 v174, v65, v65
	v_fmac_f32_e32 v175, v61, v61
	v_fmac_f32_e32 v176, v57, v57
	v_fmac_f32_e32 v177, v53, v53
	v_add_f32_e32 v174, v174, v175
	v_add_f32_e32 v176, v176, v177
	v_add_f32_e32 v178, v174, v176
	ds_bpermute_b32 v179, v131, v178
	v_permlane16_swap_b32_e32 v166, v168
	v_permlane16_swap_b32_e32 v167, v169
	v_permlane16_swap_b32_e32 v170, v172
	v_permlane16_swap_b32_e32 v171, v173
	v_add_u32_e32 v253, 0x40000, v252
	global_store_dwordx4 v253, v[166:169], s[14:15]
	global_store_dwordx4 v253, v[170:173], s[14:15] offset:256
	s_waitcnt lgkmcnt(0)
	v_add_f32_e32 v178, v178, v179
	ds_bpermute_b32 v179, v135, v178
	v_add_u32_e32 v189, 0x2000, v189
	s_waitcnt lgkmcnt(0)
	v_add_f32_e32 v178, v178, v179
	s_and_saveexec_b64 s[24:25], s[6:7]
	global_store_dword v189, v178, s[16:17]
	s_or_b64 exec, exec, s[24:25]
	s_waitcnt vmcnt(14)
	v_permlane16_swap_b32_e32 v244, v246
	v_permlane16_swap_b32_e32 v245, v247
	v_permlane16_swap_b32_e32 v248, v250
	v_permlane16_swap_b32_e32 v249, v251
	v_lshlrev_b32_e32 v166, 16, v244
	v_and_b32_e32 v167, 0xffff0000, v244
	v_lshlrev_b32_e32 v168, 16, v245
	v_and_b32_e32 v169, 0xffff0000, v245
	v_lshlrev_b32_e32 v170, 16, v246
	v_and_b32_e32 v171, 0xffff0000, v246
	v_lshlrev_b32_e32 v172, 16, v247
	v_and_b32_e32 v173, 0xffff0000, v247
	v_lshlrev_b32_e32 v174, 16, v248
	v_and_b32_e32 v175, 0xffff0000, v248
	v_lshlrev_b32_e32 v176, 16, v249
	v_and_b32_e32 v177, 0xffff0000, v249
	v_lshlrev_b32_e32 v178, 16, v250
	v_and_b32_e32 v179, 0xffff0000, v250
	v_lshlrev_b32_e32 v180, 16, v251
	v_and_b32_e32 v181, 0xffff0000, v251
	v_pk_add_f32 v[46:47], v[46:47], v[166:167]
	v_pk_add_f32 v[48:49], v[48:49], v[168:169]
	v_pk_add_f32 v[42:43], v[42:43], v[170:171]
	v_pk_add_f32 v[44:45], v[44:45], v[172:173]
	v_pk_add_f32 v[38:39], v[38:39], v[174:175]
	v_pk_add_f32 v[40:41], v[40:41], v[176:177]
	v_pk_add_f32 v[34:35], v[34:35], v[178:179]
	v_pk_add_f32 v[36:37], v[36:37], v[180:181]
	v_cvt_pk_bf16_f32 v166, v46, v47
	v_cvt_pk_bf16_f32 v167, v48, v49
	v_cvt_pk_bf16_f32 v168, v42, v43
	v_cvt_pk_bf16_f32 v169, v44, v45
	v_cvt_pk_bf16_f32 v170, v38, v39
	v_cvt_pk_bf16_f32 v171, v40, v41
	v_cvt_pk_bf16_f32 v172, v34, v35
	v_cvt_pk_bf16_f32 v173, v36, v37
	v_mul_f32_e32 v174, v46, v46
	v_mul_f32_e32 v175, v42, v42
	v_mul_f32_e32 v176, v38, v38
	v_mul_f32_e32 v177, v34, v34
	v_fmac_f32_e32 v174, v47, v47
	v_fmac_f32_e32 v175, v43, v43
	v_fmac_f32_e32 v176, v39, v39
	v_fmac_f32_e32 v177, v35, v35
	v_fmac_f32_e32 v174, v48, v48
	v_fmac_f32_e32 v175, v44, v44
	v_fmac_f32_e32 v176, v40, v40
	v_fmac_f32_e32 v177, v36, v36
	v_fmac_f32_e32 v174, v49, v49
	v_fmac_f32_e32 v175, v45, v45
	v_fmac_f32_e32 v176, v41, v41
	v_fmac_f32_e32 v177, v37, v37
	v_add_f32_e32 v174, v174, v175
	v_add_f32_e32 v176, v176, v177
	v_add_f32_e32 v178, v174, v176
	ds_bpermute_b32 v179, v131, v178
	v_permlane16_swap_b32_e32 v166, v168
	v_permlane16_swap_b32_e32 v167, v169
	v_permlane16_swap_b32_e32 v170, v172
	v_permlane16_swap_b32_e32 v171, v173
	v_add_u32_e32 v253, 0x48000, v252
	global_store_dwordx4 v253, v[166:169], s[14:15]
	global_store_dwordx4 v253, v[170:173], s[14:15] offset:256
	s_waitcnt lgkmcnt(0)
	v_add_f32_e32 v178, v178, v179
	ds_bpermute_b32 v179, v135, v178
	s_waitcnt lgkmcnt(0)
	v_add_f32_e32 v178, v178, v179
	s_and_saveexec_b64 s[24:25], s[6:7]
	global_store_dword v189, v178, s[16:17] offset:1024
	s_or_b64 exec, exec, s[24:25]
	s_waitcnt vmcnt(14)
; __device__ __forceinline__ float bf_lo(unsigned u) { return __uint_as_float(u << 16); }
; __device__ __forceinline__ float bf_hi(unsigned u) { return __uint_as_float(u & 0xffff0000u); }
; __device__ __forceinline__ unsigned pk_bf16(float lo, float hi) { const f32x2 v = {lo, hi}; const bf16x2_t b = __builtin_convertvector(v, bf16x2_t); return __builtin_bit_cast(unsigned, b); }
;     __device__ __forceinline__ void operator()(const f32x4 (&acc)[2][2][4][2], const pg8::Unit& u, int wr, int wc, int fr, int fq) const {
;     ...
;         for (int ai = 0; ai < 2; ++ai)
; #pragma unroll
;             for (int m = 0; m < 4; ++m) {
;                 const int row = row0 + ai * 128 + m * 16; const size_t off = (size_t)row * DM + col0; float q = 0.f;
;                 f32x4 r4[2][2];
;                 if (rf32) {
; #pragma unroll
;                     for (int bj = 0; bj < 2; ++bj)
; #pragma unroll
;                         for (int n = 0; n < 2; ++n) r4[bj][n] = *(const f32x4*)(rp + off + bj * 128 + n * 16);
;                 } else {
; #pragma unroll
;                     for (int bj = 0; bj < 2; ++bj)
; #pragma unroll
;                         for (int n = 0; n < 2; ++n) { const u32x2 w = *(const u32x2*)(XB + off + bj * 128 + n * 16); r4[bj][n] = (f32x4){bf_lo(w.x), bf_hi(w.x), bf_lo(w.y), bf_hi(w.y)}; }
;                 }
; #pragma unroll
;                 for (int bj = 0; bj < 2; ++bj)
; #pragma unroll
;                     for (int n = 0; n < 2; ++n) { const f32x4 x4 = r4[bj][n] + acc[ai][bj][m][n];
;                         q += (x4[0] * x4[0] + x4[1] * x4[1]) + (x4[2] * x4[2] + x4[3] * x4[3]);
;                         u32x2 w; w.x = pk_bf16(x4[0], x4[1]); w.y = pk_bf16(x4[2], x4[3]); *(u32x2*)(XB + off + bj * 128 + n * 16) = w; }
;                 q += __shfl_xor(q, 16); q += __shfl_xor(q, 32);
;                 if (fq == 0) ssq[(size_t)row * 16 + u.pn * 4 + wc] = q;
;                 if (m & 1) asm volatile("" ::: "memory");
;             }
	v_permlane16_swap_b32_e32 v204, v206
	v_permlane16_swap_b32_e32 v205, v207
	v_permlane16_swap_b32_e32 v208, v210
	v_permlane16_swap_b32_e32 v209, v211
	v_lshlrev_b32_e32 v166, 16, v204
	v_and_b32_e32 v167, 0xffff0000, v204
	v_lshlrev_b32_e32 v168, 16, v205
	v_and_b32_e32 v169, 0xffff0000, v205
	v_lshlrev_b32_e32 v170, 16, v206
	v_and_b32_e32 v171, 0xffff0000, v206
	v_lshlrev_b32_e32 v172, 16, v207
	v_and_b32_e32 v173, 0xffff0000, v207
	v_lshlrev_b32_e32 v174, 16, v208
	v_and_b32_e32 v175, 0xffff0000, v208
	v_lshlrev_b32_e32 v176, 16, v209
	v_and_b32_e32 v177, 0xffff0000, v209
	v_lshlrev_b32_e32 v178, 16, v210
	v_and_b32_e32 v179, 0xffff0000, v210
	v_lshlrev_b32_e32 v180, 16, v211
	v_and_b32_e32 v181, 0xffff0000, v211
	v_pk_add_f32 v[30:31], v[30:31], v[166:167]
	v_pk_add_f32 v[32:33], v[32:33], v[168:169]
	v_pk_add_f32 v[26:27], v[26:27], v[170:171]
	v_pk_add_f32 v[28:29], v[28:29], v[172:173]
	v_pk_add_f32 v[22:23], v[22:23], v[174:175]
	v_pk_add_f32 v[24:25], v[24:25], v[176:177]
	v_pk_add_f32 v[18:19], v[18:19], v[178:179]
	v_pk_add_f32 v[20:21], v[20:21], v[180:181]
	v_cvt_pk_bf16_f32 v166, v30, v31
	v_cvt_pk_bf16_f32 v167, v32, v33
	v_cvt_pk_bf16_f32 v168, v26, v27
	v_cvt_pk_bf16_f32 v169, v28, v29
	v_cvt_pk_bf16_f32 v170, v22, v23
	v_cvt_pk_bf16_f32 v171, v24, v25
	v_cvt_pk_bf16_f32 v172, v18, v19
	v_cvt_pk_bf16_f32 v173, v20, v21
	v_mul_f32_e32 v174, v30, v30
	v_mul_f32_e32 v175, v26, v26
	v_mul_f32_e32 v176, v22, v22
	v_mul_f32_e32 v177, v18, v18
	v_fmac_f32_e32 v174, v31, v31
	v_fmac_f32_e32 v175, v27, v27
	v_fmac_f32_e32 v176, v23, v23
	v_fmac_f32_e32 v177, v19, v19
	v_fmac_f32_e32 v174, v32, v32
	v_fmac_f32_e32 v175, v28, v28
	v_fmac_f32_e32 v176, v24, v24
	v_fmac_f32_e32 v177, v20, v20
	v_fmac_f32_e32 v174, v33, v33
	v_fmac_f32_e32 v175, v29, v29
	v_fmac_f32_e32 v176, v25, v25
	v_fmac_f32_e32 v177, v21, v21
	v_add_f32_e32 v174, v174, v175
	v_add_f32_e32 v176, v176, v177
	v_add_f32_e32 v178, v174, v176
	ds_bpermute_b32 v179, v131, v178
	v_permlane16_swap_b32_e32 v166, v168
	v_permlane16_swap_b32_e32 v167, v169
	v_permlane16_swap_b32_e32 v170, v172
	v_permlane16_swap_b32_e32 v171, v173
	v_add_u32_e32 v253, 0x50000, v252
	global_store_dwordx4 v253, v[166:169], s[14:15]
	global_store_dwordx4 v253, v[170:173], s[14:15] offset:256
	s_waitcnt lgkmcnt(0)
	v_add_f32_e32 v178, v178, v179
	ds_bpermute_b32 v179, v135, v178
	s_waitcnt lgkmcnt(0)
	v_add_f32_e32 v178, v178, v179
	s_and_saveexec_b64 s[24:25], s[6:7]
	global_store_dword v189, v178, s[16:17] offset:2048
	s_or_b64 exec, exec, s[24:25]
	s_waitcnt vmcnt(12)
	v_permlane16_swap_b32_e32 v212, v214
	v_permlane16_swap_b32_e32 v213, v215
	v_permlane16_swap_b32_e32 v216, v218
	v_permlane16_swap_b32_e32 v217, v219
	v_lshlrev_b32_e32 v166, 16, v212
	v_and_b32_e32 v167, 0xffff0000, v212
	v_lshlrev_b32_e32 v168, 16, v213
	v_and_b32_e32 v169, 0xffff0000, v213
	v_lshlrev_b32_e32 v170, 16, v214
	v_and_b32_e32 v171, 0xffff0000, v214
	v_lshlrev_b32_e32 v172, 16, v215
	v_and_b32_e32 v173, 0xffff0000, v215
	v_lshlrev_b32_e32 v174, 16, v216
	v_and_b32_e32 v175, 0xffff0000, v216
	v_lshlrev_b32_e32 v176, 16, v217
	v_and_b32_e32 v177, 0xffff0000, v217
	v_lshlrev_b32_e32 v178, 16, v218
	v_and_b32_e32 v179, 0xffff0000, v218
	v_lshlrev_b32_e32 v180, 16, v219
	v_and_b32_e32 v181, 0xffff0000, v219
	v_pk_add_f32 v[14:15], v[14:15], v[166:167]
	v_pk_add_f32 v[16:17], v[16:17], v[168:169]
	v_pk_add_f32 v[10:11], v[10:11], v[170:171]
	v_pk_add_f32 v[12:13], v[12:13], v[172:173]
	v_pk_add_f32 v[6:7], v[6:7], v[174:175]
	v_pk_add_f32 v[8:9], v[8:9], v[176:177]
	v_pk_add_f32 v[2:3], v[2:3], v[178:179]
	v_pk_add_f32 v[4:5], v[4:5], v[180:181]
	v_cvt_pk_bf16_f32 v166, v14, v15
	v_cvt_pk_bf16_f32 v167, v16, v17
	v_cvt_pk_bf16_f32 v168, v10, v11
	v_cvt_pk_bf16_f32 v169, v12, v13
	v_cvt_pk_bf16_f32 v170, v6, v7
	v_cvt_pk_bf16_f32 v171, v8, v9
	v_cvt_pk_bf16_f32 v172, v2, v3
	v_cvt_pk_bf16_f32 v173, v4, v5
	v_mul_f32_e32 v174, v14, v14
	v_mul_f32_e32 v175, v10, v10
	v_mul_f32_e32 v176, v6, v6
	v_mul_f32_e32 v177, v2, v2
	v_fmac_f32_e32 v174, v15, v15
	v_fmac_f32_e32 v175, v11, v11
	v_fmac_f32_e32 v176, v7, v7
	v_fmac_f32_e32 v177, v3, v3
	v_fmac_f32_e32 v174, v16, v16
	v_fmac_f32_e32 v175, v12, v12
	v_fmac_f32_e32 v176, v8, v8
	v_fmac_f32_e32 v177, v4, v4
	v_fmac_f32_e32 v174, v17, v17
	v_fmac_f32_e32 v175, v13, v13
	v_fmac_f32_e32 v176, v9, v9
	v_fmac_f32_e32 v177, v5, v5
	v_add_f32_e32 v174, v174, v175
	v_add_f32_e32 v176, v176, v177
	v_add_f32_e32 v178, v174, v176
	ds_bpermute_b32 v179, v131, v178
	v_permlane16_swap_b32_e32 v166, v168
	v_permlane16_swap_b32_e32 v167, v169
	v_permlane16_swap_b32_e32 v170, v172
	v_permlane16_swap_b32_e32 v171, v173
	v_add_u32_e32 v253, 0x58000, v252
	global_store_dwordx4 v253, v[166:169], s[14:15]
	global_store_dwordx4 v253, v[170:173], s[14:15] offset:256
	s_waitcnt lgkmcnt(0)
	v_add_f32_e32 v178, v178, v179
	ds_bpermute_b32 v179, v135, v178
	s_waitcnt lgkmcnt(0)
	v_add_f32_e32 v178, v178, v179
	s_and_saveexec_b64 s[24:25], s[6:7]
	global_store_dword v189, v178, s[16:17] offset:3072
	s_or_b64 exec, exec, s[24:25]
.LBB0_1909:
	s_and_b64 vcc, exec, s[8:9]
	s_mov_b64 s[8:9], -1
	s_cbranch_vccnz .LBB0_1878
	s_andn2_b64 vcc, exec, s[12:13]
	s_cbranch_vccnz .LBB0_1877
	s_barrier
	s_branch .LBB0_1877
